# P5 LayerNorm tail rows: the three partial-sum loads per chunk are requested together (same add order)
# speedup vs baseline: 1.0046x; 1.0046x over previous
; DI void ln_rows(const Params& p, int l) {
;     ...
; #pragma unroll
;       for (int j = 0; j < 4; ++j) {
;         dst[j] = *(const f32x4*)(p.R + (size_t)row * DM + lane * 4 + 256 * j);
;         if (row >= 16384) {
; #pragma unroll
;           for (int q = 0; q < 3; ++q) dst[j] += *(const f32x4*)(p.Y1 + ((size_t)q * 512 + (row - 16384)) * DM + lane * 4 + 256 * j);
;         }
;       }
;     }
;   };
;   f32x4 v[4], vn[4];
;   int row = blockIdx.x * 8 + w;
;   if (row < MT) loadrow(row, v);
.LBB0_2805:
	s_or_b64 exec, exec, s[0:1]
	v_mov_b32_e32 v0, v152
	s_waitcnt lgkmcnt(0)
	s_barrier
	v_readlane_b32 s0, v241, 48
	v_ashrrev_i32_e32 v28, 6, v0
	v_and_b32_e32 v1, 63, v0
	s_waitcnt vmcnt(0)
	v_add_u32_e32 v12, s0, v28
	s_movk_i32 s0, 0x4200
	v_mov_b32_e32 v27, 0
	v_cmp_gt_i32_e64 s[0:1], s0, v12
	v_ashrrev_i32_e32 v13, 31, v12
	v_lshlrev_b32_e32 v0, 2, v1
	v_lshlrev_b32_e32 v14, 4, v1
	v_mov_b32_e32 v26, v27
	v_mov_b32_e32 v25, v27
	v_mov_b32_e32 v24, v27
	v_mov_b32_e32 v19, v27
	v_mov_b32_e32 v18, v27
	v_mov_b32_e32 v17, v27
	v_mov_b32_e32 v16, v27
	v_mov_b32_e32 v11, v27
	v_mov_b32_e32 v10, v27
	v_mov_b32_e32 v9, v27
	v_mov_b32_e32 v8, v27
	v_mov_b32_e32 v7, v27
	v_mov_b32_e32 v6, v27
	v_mov_b32_e32 v5, v27
	v_mov_b32_e32 v4, v27
	s_and_saveexec_b64 s[4:5], s[0:1]
	s_cbranch_execz .LBB0_2815
	v_lshlrev_b64 v[4:5], 12, v[12:13]
	v_readlane_b32 s22, v240, 15
	v_readlane_b32 s23, v240, 16
	v_mov_b32_e32 v15, v3
	s_nop 0
	v_lshl_add_u64 v[4:5], s[22:23], 0, v[4:5]
	v_lshl_add_u64 v[20:21], v[4:5], 0, v[14:15]
	global_load_dwordx4 v[4:7], v[20:21], off
	v_add_u32_e32 v2, 0xffffc000, v12
	v_readlane_b32 s8, v241, 40
	s_movk_i32 s2, 0x3fff
	v_lshlrev_b64 v[8:9], 12, v[2:3]
	v_readlane_b32 s9, v241, 41
	v_cmp_lt_i32_e64 s[2:3], s2, v12
	v_lshlrev_b32_e32 v2, 2, v0
	v_lshl_add_u64 v[22:23], s[8:9], 0, v[8:9]
	v_readlane_b32 s13, v241, 45
	s_and_saveexec_b64 s[6:7], s[2:3]
	s_cbranch_execz .LBB0_2808
	v_lshl_add_u64 v[16:17], v[22:23], 0, v[2:3]
	v_add_co_u32_e32 v80, vcc, 0x200000, v16
	s_nop 1
	v_addc_co_u32_e32 v81, vcc, 0, v17, vcc
	v_add_co_u32_e32 v82, vcc, 0x400000, v16
	s_nop 1
	v_addc_co_u32_e32 v83, vcc, 0, v17, vcc
	global_load_dwordx4 v[8:11], v[16:17], off
	global_load_dwordx4 v[84:87], v[80:81], off
	global_load_dwordx4 v[88:91], v[82:83], off
	s_waitcnt vmcnt(0)
	v_pk_add_f32 v[8:9], v[4:5], v[8:9]
	v_pk_add_f32 v[10:11], v[6:7], v[10:11]
	v_pk_add_f32 v[8:9], v[84:85], v[8:9]
	v_pk_add_f32 v[10:11], v[86:87], v[10:11]
	v_pk_add_f32 v[6:7], v[90:91], v[10:11]
	v_pk_add_f32 v[4:5], v[88:89], v[8:9]
.LBB0_2808:
	s_or_b64 exec, exec, s[6:7]
	global_load_dwordx4 v[8:11], v[20:21], off offset:1024
	s_and_saveexec_b64 s[6:7], s[2:3]
	s_cbranch_execz .LBB0_2810
	v_lshl_add_u64 v[24:25], v[22:23], 0, v[2:3]
	v_add_co_u32_e32 v80, vcc, 0x200000, v24
	s_nop 1
	v_addc_co_u32_e32 v81, vcc, 0, v25, vcc
	v_add_co_u32_e32 v82, vcc, 0x400000, v24
	s_nop 1
	v_addc_co_u32_e32 v83, vcc, 0, v25, vcc
	global_load_dwordx4 v[16:19], v[24:25], off offset:1024
	global_load_dwordx4 v[84:87], v[80:81], off offset:1024
	global_load_dwordx4 v[88:91], v[82:83], off offset:1024
	s_waitcnt vmcnt(0)
	v_pk_add_f32 v[16:17], v[8:9], v[16:17]
	v_pk_add_f32 v[18:19], v[10:11], v[18:19]
	v_pk_add_f32 v[16:17], v[84:85], v[16:17]
	v_pk_add_f32 v[18:19], v[86:87], v[18:19]
	v_pk_add_f32 v[10:11], v[90:91], v[18:19]
	v_pk_add_f32 v[8:9], v[88:89], v[16:17]
.LBB0_2810:
	s_or_b64 exec, exec, s[6:7]
	global_load_dwordx4 v[16:19], v[20:21], off offset:2048
	s_and_saveexec_b64 s[6:7], s[2:3]
	s_cbranch_execz .LBB0_2812
	v_lshl_add_u64 v[30:31], v[22:23], 0, v[2:3]
	v_add_co_u32_e32 v80, vcc, 0x200000, v30
	s_nop 1
	v_addc_co_u32_e32 v81, vcc, 0, v31, vcc
	v_add_co_u32_e32 v82, vcc, 0x400000, v30
	s_nop 1
	v_addc_co_u32_e32 v83, vcc, 0, v31, vcc
	global_load_dwordx4 v[24:27], v[30:31], off offset:2048
	global_load_dwordx4 v[84:87], v[80:81], off offset:2048
	global_load_dwordx4 v[88:91], v[82:83], off offset:2048
	s_waitcnt vmcnt(0)
	v_pk_add_f32 v[24:25], v[16:17], v[24:25]
	v_pk_add_f32 v[26:27], v[18:19], v[26:27]
	v_pk_add_f32 v[24:25], v[84:85], v[24:25]
	v_pk_add_f32 v[26:27], v[86:87], v[26:27]
	v_pk_add_f32 v[18:19], v[90:91], v[26:27]
	v_pk_add_f32 v[16:17], v[88:89], v[24:25]
.LBB0_2812:
	s_or_b64 exec, exec, s[6:7]
	global_load_dwordx4 v[24:27], v[20:21], off offset:3072
	s_and_saveexec_b64 s[6:7], s[2:3]
	s_cbranch_execz .LBB0_2814
	v_lshl_add_u64 v[30:31], v[22:23], 0, v[2:3]
	v_add_co_u32_e32 v80, vcc, 0x200000, v30
	s_nop 1
	v_addc_co_u32_e32 v81, vcc, 0, v31, vcc
	v_add_co_u32_e32 v82, vcc, 0x400000, v30
	s_nop 1
	v_addc_co_u32_e32 v83, vcc, 0, v31, vcc
	global_load_dwordx4 v[20:23], v[30:31], off offset:3072
	global_load_dwordx4 v[84:87], v[80:81], off offset:3072
	global_load_dwordx4 v[88:91], v[82:83], off offset:3072
	s_waitcnt vmcnt(0)
	v_pk_add_f32 v[24:25], v[24:25], v[20:21]
	v_pk_add_f32 v[26:27], v[26:27], v[22:23]
	v_pk_add_f32 v[24:25], v[84:85], v[24:25]
	v_pk_add_f32 v[26:27], v[86:87], v[26:27]
	v_pk_add_f32 v[26:27], v[90:91], v[26:27]
	v_pk_add_f32 v[24:25], v[88:89], v[24:25]

; DI void ln_rows(const Params& p, int l) {
;     ...
; #pragma unroll
;       for (int j = 0; j < 4; ++j) {
;         dst[j] = *(const f32x4*)(p.R + (size_t)row * DM + lane * 4 + 256 * j);
;         if (row >= 16384) {
; #pragma unroll
;           for (int q = 0; q < 3; ++q) dst[j] += *(const f32x4*)(p.Y1 + ((size_t)q * 512 + (row - 16384)) * DM + lane * 4 + 256 * j);
;         }
;       }
;     }
;   };
;   f32x4 v[4], vn[4];
;   int row = blockIdx.x * 8 + w;
;   if (row < MT) loadrow(row, v);
;   for (; row < MT; row += stride) {
;     const int b = row / PP, t = row - b * PP;
;     if (row + stride < MT) loadrow(row + stride, vn);
.LBB0_2819:
	v_add_u32_e32 v1, s18, v58
	v_add_u32_e32 v2, 0x80, v1
	s_movk_i32 s0, 0x4200
	v_cmp_gt_i32_e32 vcc, s0, v2
	s_movk_i32 s0, 0x41ff
	v_cmp_lt_i32_e64 s[0:1], s0, v2
	s_and_saveexec_b64 s[8:9], vcc
	s_cbranch_execz .LBB0_2827
	v_lshl_add_u64 v[32:33], v[40:41], 0, v[44:45]
	global_load_dwordx4 v[12:15], v[32:33], off
	s_movk_i32 s2, 0x3fff
	v_cmp_lt_i32_e64 s[2:3], s2, v2
	v_add_u32_e32 v2, 0xffffc080, v1
	v_lshlrev_b64 v[28:29], 12, v[2:3]
	s_and_saveexec_b64 s[10:11], s[2:3]
	s_cbranch_execz .LBB0_2822
	v_readlane_b32 s20, v241, 40
	v_readlane_b32 s21, v241, 41
	v_lshlrev_b32_e32 v2, 2, v0
	v_readlane_b32 s22, v241, 42
	v_lshl_add_u64 v[20:21], s[20:21], 0, v[28:29]
	v_lshl_add_u64 v[30:31], v[20:21], 0, v[2:3]
	v_add_co_u32_e32 v80, vcc, 0x200000, v30
	s_nop 1
	v_addc_co_u32_e32 v81, vcc, 0, v31, vcc
	v_add_co_u32_e32 v82, vcc, 0x400000, v30
	s_nop 1
	v_addc_co_u32_e32 v83, vcc, 0, v31, vcc
	global_load_dwordx4 v[20:23], v[30:31], off
	global_load_dwordx4 v[84:87], v[80:81], off
	global_load_dwordx4 v[88:91], v[82:83], off
	v_readlane_b32 s23, v241, 43
	v_readlane_b32 s27, v241, 47
	s_waitcnt vmcnt(0)
	v_pk_add_f32 v[20:21], v[12:13], v[20:21]
	v_pk_add_f32 v[22:23], v[14:15], v[22:23]
	v_pk_add_f32 v[20:21], v[84:85], v[20:21]
	v_pk_add_f32 v[22:23], v[86:87], v[22:23]
	v_pk_add_f32 v[14:15], v[90:91], v[22:23]
	v_pk_add_f32 v[12:13], v[88:89], v[20:21]
.LBB0_2822:
	s_or_b64 exec, exec, s[10:11]
	global_load_dwordx4 v[20:23], v[32:33], off offset:1024
	v_lshl_add_u64 v[50:51], v[42:43], 0, v[28:29]
	s_and_saveexec_b64 s[10:11], s[2:3]
	s_cbranch_execz .LBB0_2850
	v_add_co_u32_e32 v80, vcc, 0x200000, v50
	s_nop 1
	v_addc_co_u32_e32 v81, vcc, 0, v51, vcc
	v_add_co_u32_e32 v82, vcc, 0x400000, v50
	s_nop 1
	v_addc_co_u32_e32 v83, vcc, 0, v51, vcc
	global_load_dwordx4 v[28:31], v[50:51], off offset:1024
	global_load_dwordx4 v[84:87], v[80:81], off offset:1024
	global_load_dwordx4 v[88:91], v[82:83], off offset:1024
	s_waitcnt vmcnt(0)
	v_pk_add_f32 v[28:29], v[20:21], v[28:29]
	v_pk_add_f32 v[30:31], v[22:23], v[30:31]
	v_pk_add_f32 v[28:29], v[84:85], v[28:29]
	v_pk_add_f32 v[30:31], v[86:87], v[30:31]
	v_pk_add_f32 v[22:23], v[90:91], v[30:31]
	v_pk_add_f32 v[20:21], v[88:89], v[28:29]
	s_or_b64 exec, exec, s[10:11]
	global_load_dwordx4 v[28:31], v[32:33], off offset:2048
	s_and_saveexec_b64 s[10:11], s[2:3]
	s_cbranch_execnz .LBB0_2851

; DI void ln_rows(const Params& p, int l) {
;     ...
;         dst[j] = *(const f32x4*)(p.R + (size_t)row * DM + lane * 4 + 256 * j);
;         if (row >= 16384) {
; #pragma unroll
;           for (int q = 0; q < 3; ++q) dst[j] += *(const f32x4*)(p.Y1 + ((size_t)q * 512 + (row - 16384)) * DM + lane * 4 + 256 * j);
;         }
.LBB0_2825:
	v_add_co_u32_e32 v80, vcc, 0x200000, v50
	s_nop 1
	v_addc_co_u32_e32 v81, vcc, 0, v51, vcc
	v_add_co_u32_e32 v82, vcc, 0x400000, v50
	s_nop 1
	v_addc_co_u32_e32 v83, vcc, 0, v51, vcc
	global_load_dwordx4 v[52:55], v[50:51], off offset:3072
	global_load_dwordx4 v[84:87], v[80:81], off offset:3072
	global_load_dwordx4 v[88:91], v[82:83], off offset:3072
	s_waitcnt vmcnt(0)
	v_pk_add_f32 v[52:53], v[32:33], v[52:53]
	v_pk_add_f32 v[54:55], v[34:35], v[54:55]
	v_pk_add_f32 v[52:53], v[84:85], v[52:53]
	v_pk_add_f32 v[54:55], v[86:87], v[54:55]
	v_pk_add_f32 v[34:35], v[90:91], v[54:55]
	v_pk_add_f32 v[32:33], v[88:89], v[52:53]

; DI void ln_rows(const Params& p, int l) {
;     ...
;         dst[j] = *(const f32x4*)(p.R + (size_t)row * DM + lane * 4 + 256 * j);
;         if (row >= 16384) {
; #pragma unroll
;           for (int q = 0; q < 3; ++q) dst[j] += *(const f32x4*)(p.Y1 + ((size_t)q * 512 + (row - 16384)) * DM + lane * 4 + 256 * j);
;         }
.LBB0_2851:
	v_add_co_u32_e32 v80, vcc, 0x200000, v50
	s_nop 1
	v_addc_co_u32_e32 v81, vcc, 0, v51, vcc
	v_add_co_u32_e32 v82, vcc, 0x400000, v50
	s_nop 1
	v_addc_co_u32_e32 v83, vcc, 0, v51, vcc
	global_load_dwordx4 v[52:55], v[50:51], off offset:2048
	global_load_dwordx4 v[84:87], v[80:81], off offset:2048
	global_load_dwordx4 v[88:91], v[82:83], off offset:2048
	s_waitcnt vmcnt(0)
	v_pk_add_f32 v[52:53], v[28:29], v[52:53]
	v_pk_add_f32 v[34:35], v[30:31], v[54:55]
	v_pk_add_f32 v[52:53], v[84:85], v[52:53]
	v_pk_add_f32 v[34:35], v[86:87], v[34:35]
	v_pk_add_f32 v[30:31], v[90:91], v[34:35]
	v_pk_add_f32 v[28:29], v[88:89], v[52:53]
	s_or_b64 exec, exec, s[10:11]
	global_load_dwordx4 v[32:35], v[32:33], off offset:3072
	s_and_saveexec_b64 s[10:11], s[2:3]
	s_cbranch_execnz .LBB0_2825
	s_branch .LBB0_2826
